# dense-attn loop: phase-B LDS waits consolidated (2 per step instead of 8)
# baseline (speedup 1.0000x reference)
.LBB0_450:
	s_mov_b32 s30, s29
	s_mov_b32 s29, s21
	v_add_u32_e32 v128, s31, v199
	ds_read_b64_tr_b16 v[204:205], v128 offset:24576
	ds_read_b64_tr_b16 v[206:207], v128 offset:25088
	v_add_f32_e32 v84, v64, v65
	v_add_f32_e32 v84, v66, v84
	v_add_f32_e32 v84, v67, v84
	v_add_f32_e32 v84, v68, v84
	v_add_f32_e32 v84, v69, v84
	v_cvt_pk_bf16_f32 v154, v64, v65
	v_cvt_pk_bf16_f32 v155, v66, v67
	v_mfma_f32_32x32x16_bf16 v[96:111], v[80:83], v[158:161], v[32:47]
	ds_read_b64_tr_b16 v[64:65], v128 offset:28672
	ds_read_b64_tr_b16 v[66:67], v128 offset:29184
	v_add_f32_e32 v80, v70, v84
	v_add_f32_e32 v80, v71, v80
	v_add_f32_e32 v80, v72, v80
	v_add_f32_e32 v130, v73, v80
	v_mfma_f32_32x32x16_bf16 v[80:95], v[166:169], v[158:161], v[32:47]
	v_cvt_pk_bf16_f32 v156, v68, v69
	v_cvt_pk_bf16_f32 v157, v70, v71
	ds_read_b64_tr_b16 v[68:69], v128 offset:25600
	ds_read_b64_tr_b16 v[70:71], v128 offset:26112
	v_add_f32_e32 v130, v74, v130
	v_add_f32_e32 v130, v75, v130
	v_add_f32_e32 v130, v76, v130
	v_add_f32_e32 v130, v77, v130
	v_cvt_pk_bf16_f32 v146, v72, v73
	v_cvt_pk_bf16_f32 v147, v74, v75
	v_mfma_f32_32x32x16_bf16 v[96:111], v[170:173], v[150:153], v[96:111]
	ds_read_b64_tr_b16 v[72:73], v128 offset:29696
	ds_read_b64_tr_b16 v[74:75], v128 offset:30208
	v_mfma_f32_32x32x16_bf16 v[80:95], v[162:165], v[150:153], v[80:95]
	v_add_f32_e32 v130, v78, v130
	v_add_f32_e32 v130, v79, v130
	v_add_f32_e32 v130, v48, v130
	v_add_f32_e32 v130, v49, v130
	v_cvt_pk_bf16_f32 v148, v76, v77
	v_cvt_pk_bf16_f32 v149, v78, v79
	ds_read_b64_tr_b16 v[76:77], v128 offset:26624
	ds_read_b64_tr_b16 v[78:79], v128 offset:27136
	v_mfma_f32_32x32x16_bf16 v[96:111], v[124:127], v[142:145], v[96:111]
	v_add_f32_e32 v124, v50, v130
	v_add_f32_e32 v124, v51, v124
	v_add_f32_e32 v124, v52, v124
	v_add_f32_e32 v124, v53, v124
	v_cvt_pk_bf16_f32 v138, v48, v49
	v_cvt_pk_bf16_f32 v139, v50, v51
	ds_read_b64_tr_b16 v[48:49], v128 offset:30720
	ds_read_b64_tr_b16 v[50:51], v128 offset:31232
	v_mfma_f32_32x32x16_bf16 v[80:95], v[120:123], v[142:145], v[80:95]
	v_add_f32_e32 v120, v54, v124
	v_add_f32_e32 v120, v55, v120
	v_add_f32_e32 v120, v56, v120
	v_add_f32_e32 v120, v57, v120
	v_cvt_pk_bf16_f32 v140, v52, v53
	v_cvt_pk_bf16_f32 v141, v54, v55
	ds_read_b64_tr_b16 v[52:53], v128 offset:27648
	ds_read_b64_tr_b16 v[54:55], v128 offset:28160
	v_mfma_f32_32x32x16_bf16 v[96:111], v[116:119], v[134:137], v[96:111]
	v_add_f32_e32 v116, v58, v120
	v_add_f32_e32 v116, v59, v116
	v_add_f32_e32 v116, v60, v116
	v_add_f32_e32 v116, v61, v116
	v_cvt_pk_bf16_f32 v130, v56, v57
	v_cvt_pk_bf16_f32 v131, v58, v59
	ds_read_b64_tr_b16 v[56:57], v128 offset:31744
	ds_read_b64_tr_b16 v[58:59], v128 offset:32256
	v_mfma_f32_32x32x16_bf16 v[80:95], v[112:115], v[134:137], v[80:95]
	v_add_f32_e32 v112, v62, v116
	v_add_f32_e32 v112, v63, v112
	v_cvt_pk_bf16_f32 v132, v60, v61
	v_cvt_pk_bf16_f32 v133, v62, v63
	s_add_i32 m0, s21, s5
	s_nop 0
	global_load_lds_dwordx4 v216, s[98:99]
	s_add_i32 m0, s30, s4
	s_nop 0
	global_load_lds_dwordx4 v217, s[100:101]
	v_add_f32_e32 v128, v203, v112
	s_waitcnt lgkmcnt(2)
	v_mfma_f32_32x32x16_bf16 v[0:15], v[154:157], v[204:207], v[0:15]
	v_exp_f32_e32 v96, v96
	v_exp_f32_e32 v97, v97
	v_exp_f32_e32 v98, v98
	v_exp_f32_e32 v99, v99
	v_mfma_f32_32x32x16_bf16 v[16:31], v[154:157], v[64:67], v[16:31]
	v_exp_f32_e32 v100, v100
	v_exp_f32_e32 v101, v101
	v_exp_f32_e32 v102, v102
	v_exp_f32_e32 v103, v103
	v_add_u32_e32 v64, s30, v200
	ds_read_b128 v[60:63], v64
	ds_read_b128 v[116:119], v64 offset:512
	v_mfma_f32_32x32x16_bf16 v[0:15], v[146:149], v[68:71], v[0:15]
	v_exp_f32_e32 v104, v104
	v_exp_f32_e32 v105, v105
	v_exp_f32_e32 v106, v106
	v_exp_f32_e32 v107, v107
	ds_read_b128 v[120:123], v64 offset:2048
	ds_read_b128 v[124:127], v64 offset:2560
	v_mfma_f32_32x32x16_bf16 v[16:31], v[146:149], v[72:75], v[16:31]
	v_exp_f32_e32 v108, v108
	v_exp_f32_e32 v109, v109
	v_exp_f32_e32 v110, v110
	v_exp_f32_e32 v111, v111
	ds_read_b128 v[162:165], v64 offset:4096
	ds_read_b128 v[166:169], v64 offset:4608
	v_mfma_f32_32x32x16_bf16 v[0:15], v[138:141], v[76:79], v[0:15]
	v_exp_f32_e32 v80, v80
	v_exp_f32_e32 v81, v81
	v_exp_f32_e32 v82, v82
	v_exp_f32_e32 v83, v83
	ds_read_b128 v[170:173], v64 offset:6144
	ds_read_b128 v[112:115], v64 offset:6656
	v_mfma_f32_32x32x16_bf16 v[16:31], v[138:141], v[48:51], v[16:31]
	v_exp_f32_e32 v84, v84
	v_exp_f32_e32 v85, v85
	v_exp_f32_e32 v86, v86
	v_exp_f32_e32 v87, v87
	v_mfma_f32_32x32x16_bf16 v[0:15], v[130:133], v[52:55], v[0:15]
	v_exp_f32_e32 v88, v88
	v_exp_f32_e32 v89, v89
	v_exp_f32_e32 v90, v90
	v_exp_f32_e32 v91, v91
	s_waitcnt lgkmcnt(8)
	v_mfma_f32_32x32x16_bf16 v[16:31], v[130:133], v[56:59], v[16:31]
	v_exp_f32_e32 v92, v92
	v_exp_f32_e32 v93, v93
	v_exp_f32_e32 v94, v94
	v_exp_f32_e32 v95, v95
	s_waitcnt vmcnt(2) lgkmcnt(0)
	s_barrier
; #define WAIT_BAR(N) asm volatile("s_waitcnt vmcnt(" #N ") lgkmcnt(0)\n\ts_barrier":::"memory")
;   #define RESC() do{}while(0)
;   #define ROT() do{sl_prev=sl_cur;sl_cur=sl_next;sl_next=(sl_next==(NSLOT-1)*SLOTB)?0:sl_next+SLOTB;}while(0)
; template<int THRL> __device__ __forceinline__ void attn_unit(int b,int h,int qb,const bf16*Q,const bf16*__restrict__ K,const bf16*__restrict__ V,bf16*O,float*gssrow,float mref,char*shm){
;     ...
;   if(wid>=4)__builtin_amdgcn_s_setprio(1);
;   int t=1;
;     ...
;   for(;t+5<NT;t+=2){
;     STEP(pB0,pB1,pA0,pA1,t,true,true,true);     WAIT_BAR(2); RESC(); ROT();
;     STEP(pA0,pA1,pB0,pB1,t+1,true,true,true);   WAIT_BAR(2); RESC(); ROT();
;   }
	s_add_i32 s21, s30, 0x2000
	s_cmpk_lg_i32 s30, 0x4000
	s_cselect_b32 s21, s21, 0
	v_add_u32_e32 v174, s29, v199
	ds_read_b64_tr_b16 v[204:205], v174 offset:24576
	ds_read_b64_tr_b16 v[206:207], v174 offset:25088
	v_mfma_f32_32x32x16_bf16 v[64:79], v[60:63], v[158:161], v[32:47]
	v_add_f32_e32 v48, v96, v97
	v_add_f32_e32 v48, v98, v48
	v_add_f32_e32 v48, v99, v48
	v_add_f32_e32 v48, v100, v48
	v_add_f32_e32 v48, v101, v48
	v_cvt_pk_bf16_f32 v154, v96, v97
	v_cvt_pk_bf16_f32 v155, v98, v99
	ds_read_b64_tr_b16 v[96:97], v174 offset:28672
	ds_read_b64_tr_b16 v[98:99], v174 offset:29184
	v_add_f32_e32 v48, v102, v48
	v_add_f32_e32 v48, v103, v48
	v_add_f32_e32 v48, v104, v48
	v_add_f32_e32 v130, v105, v48
	v_mfma_f32_32x32x16_bf16 v[48:63], v[116:119], v[158:161], v[32:47]
	v_cvt_pk_bf16_f32 v156, v100, v101
	v_cvt_pk_bf16_f32 v157, v102, v103
	ds_read_b64_tr_b16 v[100:101], v174 offset:25600
	ds_read_b64_tr_b16 v[102:103], v174 offset:26112
	v_mfma_f32_32x32x16_bf16 v[64:79], v[120:123], v[150:153], v[64:79]
	v_add_f32_e32 v116, v106, v130
	v_add_f32_e32 v116, v107, v116
	v_add_f32_e32 v116, v108, v116
	v_add_f32_e32 v116, v109, v116
	v_cvt_pk_bf16_f32 v146, v104, v105
	v_cvt_pk_bf16_f32 v147, v106, v107
	ds_read_b64_tr_b16 v[104:105], v174 offset:29696
	ds_read_b64_tr_b16 v[106:107], v174 offset:30208
	v_mfma_f32_32x32x16_bf16 v[48:63], v[124:127], v[150:153], v[48:63]
	v_add_f32_e32 v116, v110, v116
	v_add_f32_e32 v116, v111, v116
	v_add_f32_e32 v116, v80, v116
	v_add_f32_e32 v116, v81, v116
	v_cvt_pk_bf16_f32 v148, v108, v109
	v_cvt_pk_bf16_f32 v149, v110, v111
	ds_read_b64_tr_b16 v[108:109], v174 offset:26624
	ds_read_b64_tr_b16 v[110:111], v174 offset:27136
	v_mfma_f32_32x32x16_bf16 v[64:79], v[162:165], v[142:145], v[64:79]
	v_add_f32_e32 v116, v82, v116
	v_add_f32_e32 v116, v83, v116
	v_add_f32_e32 v116, v84, v116
	v_add_f32_e32 v116, v85, v116
	v_cvt_pk_bf16_f32 v138, v80, v81
	v_cvt_pk_bf16_f32 v139, v82, v83
	ds_read_b64_tr_b16 v[208:209], v174 offset:30720
	ds_read_b64_tr_b16 v[210:211], v174 offset:31232
	v_mfma_f32_32x32x16_bf16 v[48:63], v[166:169], v[142:145], v[48:63]
	v_add_f32_e32 v80, v86, v116
	v_add_f32_e32 v80, v87, v80
	v_add_f32_e32 v80, v88, v80
	v_add_f32_e32 v80, v89, v80
	v_cvt_pk_bf16_f32 v140, v84, v85
	v_cvt_pk_bf16_f32 v141, v86, v87
	ds_read_b64_tr_b16 v[84:85], v174 offset:27648
	ds_read_b64_tr_b16 v[86:87], v174 offset:28160
	v_mfma_f32_32x32x16_bf16 v[64:79], v[170:173], v[134:137], v[64:79]
	v_add_f32_e32 v80, v90, v80
	v_add_f32_e32 v80, v91, v80
	v_add_f32_e32 v80, v92, v80
	v_add_f32_e32 v80, v93, v80
	v_cvt_pk_bf16_f32 v130, v88, v89
	v_cvt_pk_bf16_f32 v131, v90, v91
	ds_read_b64_tr_b16 v[88:89], v174 offset:31744
	ds_read_b64_tr_b16 v[90:91], v174 offset:32256
	v_mfma_f32_32x32x16_bf16 v[48:63], v[112:115], v[134:137], v[48:63]
	v_add_f32_e32 v80, v94, v80
	v_add_f32_e32 v80, v95, v80
	v_cvt_pk_bf16_f32 v132, v92, v93
	v_cvt_pk_bf16_f32 v133, v94, v95
	s_mov_b64 s[48:49], 0x10000
	v_add_f32_e32 v203, v128, v80
	s_add_i32 m0, s30, s5
	s_nop 0
	global_load_lds_dwordx4 v218, s[98:99]
	s_add_i32 m0, s21, s4
	s_nop 0
	global_load_lds_dwordx4 v219, s[100:101]
	s_waitcnt lgkmcnt(2)
	v_mfma_f32_32x32x16_bf16 v[0:15], v[154:157], v[204:207], v[0:15]
	v_exp_f32_e32 v64, v64
	v_exp_f32_e32 v65, v65
	v_exp_f32_e32 v66, v66
	v_exp_f32_e32 v67, v67
	v_mfma_f32_32x32x16_bf16 v[16:31], v[154:157], v[96:99], v[16:31]
	v_exp_f32_e32 v68, v68
	v_exp_f32_e32 v69, v69
	v_exp_f32_e32 v70, v70
	v_exp_f32_e32 v71, v71
	v_add_u32_e32 v92, s21, v200
	ds_read_b128 v[80:83], v92
	ds_read_b128 v[166:169], v92 offset:512
	v_mfma_f32_32x32x16_bf16 v[0:15], v[146:149], v[100:103], v[0:15]
	v_exp_f32_e32 v72, v72
	v_exp_f32_e32 v73, v73
	v_exp_f32_e32 v74, v74
	v_exp_f32_e32 v75, v75
	ds_read_b128 v[170:173], v92 offset:2048
	ds_read_b128 v[162:165], v92 offset:2560
	v_mfma_f32_32x32x16_bf16 v[16:31], v[146:149], v[104:107], v[16:31]
	v_exp_f32_e32 v76, v76
	v_exp_f32_e32 v77, v77
	v_exp_f32_e32 v78, v78
	v_exp_f32_e32 v79, v79
	ds_read_b128 v[124:127], v92 offset:4096
	ds_read_b128 v[120:123], v92 offset:4608
	v_mfma_f32_32x32x16_bf16 v[0:15], v[138:141], v[108:111], v[0:15]
	v_exp_f32_e32 v48, v48
	v_exp_f32_e32 v49, v49
	v_exp_f32_e32 v50, v50
	v_exp_f32_e32 v51, v51
	ds_read_b128 v[116:119], v92 offset:6144
	ds_read_b128 v[112:115], v92 offset:6656
	v_mfma_f32_32x32x16_bf16 v[16:31], v[138:141], v[208:211], v[16:31]
	v_exp_f32_e32 v52, v52
	v_exp_f32_e32 v53, v53
	v_exp_f32_e32 v54, v54
	v_exp_f32_e32 v55, v55
	v_mfma_f32_32x32x16_bf16 v[0:15], v[130:133], v[84:87], v[0:15]
	v_exp_f32_e32 v56, v56
	v_exp_f32_e32 v57, v57
	v_exp_f32_e32 v58, v58
	v_exp_f32_e32 v59, v59
	s_waitcnt lgkmcnt(8)
	v_mfma_f32_32x32x16_bf16 v[16:31], v[130:133], v[88:91], v[16:31]
	v_exp_f32_e32 v60, v60
	v_exp_f32_e32 v61, v61
	v_exp_f32_e32 v62, v62
	v_exp_f32_e32 v63, v63
	s_add_i32 s29, s21, 0x2000
	s_waitcnt vmcnt(2) lgkmcnt(0)
	s_barrier
	s_add_u32 s98, s98, 0x8000
	s_addc_u32 s99, s99, 0
	s_add_u32 s100, s100, 0x8000
	s_addc_u32 s101, s101, 0
	s_cmpk_lg_i32 s21, 0x4000
	s_cselect_b32 s29, s29, 0
	s_add_i32 s20, s20, 2
	s_cmpk_gt_u32 s20, 0xf8
	s_mov_b32 s31, s30
	s_cbranch_scc0 .LBB0_450
;   #define RESC() do{}while(0)
;   #define ROT() do{sl_prev=sl_cur;sl_cur=sl_next;sl_next=(sl_next==(NSLOT-1)*SLOTB)?0:sl_next+SLOTB;}while(0)
;   #define ENDW(tt) do{ if((tt)+3<NT){WAIT_BAR(2);} else if((tt)+2<NT){WAIT_BAR(1);} else {WAIT_BAR(0);} }while(0)
; template<int THRL> __device__ __forceinline__ void attn_unit(int b,int h,int qb,const bf16*Q,const bf16*__restrict__ K,const bf16*__restrict__ V,bf16*O,float*gssrow,float mref,char*shm){
;     ...
;   for(;t+1<NT;t+=2){
;     STEP(pB0,pB1,pA0,pA1,t,(t+3<NT),(t+1<NT),(t+1<NT));       ENDW(t);   RESC(); ROT();
;     STEP(pA0,pA1,pB0,pB1,t+1,(t+4<NT),(t+2<NT),(t+2<NT));     ENDW(t+1); RESC(); ROT();
	s_and_b32 s15, s15, 0x3fffffc0
	s_cmp_lg_u32 0, -1
	s_cselect_b32 s20, 0, 0
	s_lshl_b32 s15, s15, 2
	s_addk_i32 s20, 0x6000
	s_add_i32 s15, s15, 0
	v_add3_u32 v128, v202, s20, v201
	v_add_u32_e32 v174, s30, v199
	ds_read_b64_tr_b16 v[190:191], v174 offset:24576
	ds_read_b64_tr_b16 v[192:193], v174 offset:25088
	v_add_f32_e32 v84, v64, v65
	v_add_f32_e32 v84, v66, v84
	v_add_f32_e32 v84, v67, v84
	v_add_f32_e32 v84, v68, v84
	v_add_f32_e32 v84, v69, v84
	v_cvt_pk_bf16_f32 v154, v64, v65
	v_cvt_pk_bf16_f32 v155, v66, v67
	s_waitcnt lgkmcnt(9)
	v_mfma_f32_32x32x16_bf16 v[96:111], v[80:83], v[158:161], v[32:47]
	ds_read_b64_tr_b16 v[64:65], v174 offset:28672
	ds_read_b64_tr_b16 v[66:67], v174 offset:29184
	v_add_f32_e32 v80, v70, v84
	v_add_f32_e32 v80, v71, v80
	v_add_f32_e32 v80, v72, v80
	v_add_f32_e32 v130, v73, v80
	v_cvt_pk_bf16_f32 v156, v68, v69
	v_cvt_pk_bf16_f32 v157, v70, v71
	s_waitcnt lgkmcnt(10)
	v_mfma_f32_32x32x16_bf16 v[80:95], v[166:169], v[158:161], v[32:47]
	ds_read_b64_tr_b16 v[68:69], v174 offset:25600
	ds_read_b64_tr_b16 v[70:71], v174 offset:26112
	v_add_f32_e32 v130, v74, v130
	v_add_f32_e32 v130, v75, v130
	v_add_f32_e32 v130, v76, v130
	v_add_f32_e32 v130, v77, v130
	v_cvt_pk_bf16_f32 v146, v72, v73
	v_cvt_pk_bf16_f32 v147, v74, v75
	s_waitcnt lgkmcnt(11)
	v_mfma_f32_32x32x16_bf16 v[96:111], v[170:173], v[150:153], v[96:111]
	ds_read_b64_tr_b16 v[72:73], v174 offset:29696
	ds_read_b64_tr_b16 v[74:75], v174 offset:30208
	v_add_f32_e32 v130, v78, v130
	v_add_f32_e32 v130, v79, v130
	v_add_f32_e32 v130, v48, v130
	v_add_f32_e32 v130, v49, v130
	v_cvt_pk_bf16_f32 v148, v76, v77
	v_cvt_pk_bf16_f32 v149, v78, v79
	s_waitcnt lgkmcnt(12)
	v_mfma_f32_32x32x16_bf16 v[80:95], v[162:165], v[150:153], v[80:95]
	ds_read_b64_tr_b16 v[76:77], v174 offset:26624
	ds_read_b64_tr_b16 v[78:79], v174 offset:27136
	s_waitcnt lgkmcnt(13)
	v_mfma_f32_32x32x16_bf16 v[96:111], v[124:127], v[142:145], v[96:111]
	v_add_f32_e32 v124, v50, v130
	v_add_f32_e32 v124, v51, v124
	v_add_f32_e32 v124, v52, v124
	v_add_f32_e32 v124, v53, v124
	v_cvt_pk_bf16_f32 v138, v48, v49
	v_cvt_pk_bf16_f32 v139, v50, v51
	ds_read_b64_tr_b16 v[48:49], v174 offset:30720
	ds_read_b64_tr_b16 v[50:51], v174 offset:31232
	s_waitcnt lgkmcnt(14)
	v_mfma_f32_32x32x16_bf16 v[80:95], v[120:123], v[142:145], v[80:95]
	v_add_f32_e32 v120, v54, v124
	v_add_f32_e32 v120, v55, v120
	v_add_f32_e32 v120, v56, v120
	v_add_f32_e32 v120, v57, v120
	v_cvt_pk_bf16_f32 v140, v52, v53
	v_cvt_pk_bf16_f32 v141, v54, v55
	ds_read_b64_tr_b16 v[52:53], v174 offset:27648
	ds_read_b64_tr_b16 v[54:55], v174 offset:28160
	s_waitcnt lgkmcnt(14)
	v_mfma_f32_32x32x16_bf16 v[96:111], v[116:119], v[134:137], v[96:111]
	v_add_f32_e32 v116, v58, v120
	v_add_f32_e32 v116, v59, v116
	v_add_f32_e32 v116, v60, v116
	v_add_f32_e32 v116, v61, v116
	v_cvt_pk_bf16_f32 v130, v56, v57
	v_cvt_pk_bf16_f32 v131, v58, v59
	ds_read_b64_tr_b16 v[56:57], v174 offset:31744
	ds_read_b64_tr_b16 v[58:59], v174 offset:32256
	v_mfma_f32_32x32x16_bf16 v[80:95], v[112:115], v[134:137], v[80:95]
	v_add_f32_e32 v112, v62, v116
	v_add_f32_e32 v112, v63, v112
	v_add_f32_e32 v112, 0, v112
	v_cvt_pk_bf16_f32 v132, v60, v61
	v_cvt_pk_bf16_f32 v133, v62, v63
	s_mov_b64 s[12:13], 0x3f8000
	s_add_i32 s20, s21, s5
	v_lshl_add_u64 v[60:61], v[188:189], 0, s[12:13]
	s_mov_b32 s30, m0
	s_mov_b32 m0, s20
	s_nop 0
	global_load_lds_dwordx4 v[60:61], off
	s_mov_b32 m0, s30
	s_mov_b64 s[30:31], 0x3f0000
	v_lshl_add_u64 v[60:61], v[186:187], 0, s[30:31]
	s_add_i32 s20, s29, s4
	s_mov_b32 s30, m0
	s_mov_b32 m0, s20
	s_nop 0
	global_load_lds_dwordx4 v[60:61], off
	s_mov_b32 m0, s30
	v_add_f32_e32 v174, v203, v112
	s_waitcnt lgkmcnt(14)
	v_mfma_f32_32x32x16_bf16 v[0:15], v[154:157], v[190:193], v[0:15]
	v_exp_f32_e32 v96, v96
	v_exp_f32_e32 v97, v97
	v_exp_f32_e32 v98, v98
	v_exp_f32_e32 v99, v99
	s_waitcnt lgkmcnt(12)
	v_mfma_f32_32x32x16_bf16 v[16:31], v[154:157], v[64:67], v[16:31]
	v_exp_f32_e32 v100, v100
	v_exp_f32_e32 v101, v101
	v_exp_f32_e32 v102, v102
	v_exp_f32_e32 v103, v103
	v_add_u32_e32 v64, s29, v200
	ds_read_b128 v[60:63], v64
	ds_read_b128 v[162:165], v64 offset:512
	s_waitcnt lgkmcnt(12)
	v_mfma_f32_32x32x16_bf16 v[0:15], v[146:149], v[68:71], v[0:15]
	v_exp_f32_e32 v104, v104
	v_exp_f32_e32 v105, v105
	v_exp_f32_e32 v106, v106
	v_exp_f32_e32 v107, v107
	ds_read_b128 v[68:71], v64 offset:2048
	ds_read_b128 v[166:169], v64 offset:2560
	s_waitcnt lgkmcnt(12)
	v_mfma_f32_32x32x16_bf16 v[16:31], v[146:149], v[72:75], v[16:31]
	v_exp_f32_e32 v108, v108
	v_exp_f32_e32 v109, v109
	v_exp_f32_e32 v110, v110
	v_exp_f32_e32 v111, v111
	ds_read_b128 v[72:75], v64 offset:4096
	ds_read_b128 v[170:173], v64 offset:4608
	s_waitcnt lgkmcnt(12)
	v_mfma_f32_32x32x16_bf16 v[0:15], v[138:141], v[76:79], v[0:15]
	v_exp_f32_e32 v80, v80
	v_exp_f32_e32 v81, v81
	v_exp_f32_e32 v82, v82
	v_exp_f32_e32 v83, v83
	ds_read_b128 v[76:79], v64 offset:6144
	ds_read_b128 v[64:67], v64 offset:6656
	s_waitcnt lgkmcnt(12)
	v_mfma_f32_32x32x16_bf16 v[16:31], v[138:141], v[48:51], v[16:31]
	v_exp_f32_e32 v84, v84
	v_exp_f32_e32 v85, v85
	v_exp_f32_e32 v86, v86
	v_exp_f32_e32 v87, v87
	s_waitcnt lgkmcnt(10)
	v_mfma_f32_32x32x16_bf16 v[0:15], v[130:133], v[52:55], v[0:15]
	v_exp_f32_e32 v88, v88
	v_exp_f32_e32 v89, v89
	v_exp_f32_e32 v90, v90
	v_exp_f32_e32 v91, v91
	s_waitcnt lgkmcnt(8)
	v_mfma_f32_32x32x16_bf16 v[16:31], v[130:133], v[56:59], v[16:31]
	v_exp_f32_e32 v92, v92
	v_exp_f32_e32 v93, v93
	v_exp_f32_e32 v94, v94
	v_exp_f32_e32 v95, v95
	s_waitcnt vmcnt(2) lgkmcnt(0)
	s_barrier
;   #define RESC() do{}while(0)
;   #define ROT() do{sl_prev=sl_cur;sl_cur=sl_next;sl_next=(sl_next==(NSLOT-1)*SLOTB)?0:sl_next+SLOTB;}while(0)
;   #define ENDW(tt) do{ if((tt)+3<NT){WAIT_BAR(2);} else if((tt)+2<NT){WAIT_BAR(1);} else {WAIT_BAR(0);} }while(0)
; template<int THRL> __device__ __forceinline__ void attn_unit(int b,int h,int qb,const bf16*Q,const bf16*__restrict__ K,const bf16*__restrict__ V,bf16*O,float*gssrow,float mref,char*shm){
;     ...
;   for(;t+1<NT;t+=2){
;     STEP(pB0,pB1,pA0,pA1,t,(t+3<NT),(t+1<NT),(t+1<NT));       ENDW(t);   RESC(); ROT();
;     STEP(pA0,pA1,pB0,pB1,t+1,(t+4<NT),(t+2<NT),(t+2<NT));     ENDW(t+1); RESC(); ROT();
	s_add_i32 s20, s29, 0x2000
	s_cmpk_lg_i32 s29, 0x4000
	s_cselect_b32 s20, s20, 0
	v_add_u32_e32 v175, s21, v199
	ds_read_b64_tr_b16 v[190:191], v175 offset:24576
	ds_read_b64_tr_b16 v[192:193], v175 offset:25088
	v_add_f32_e32 v48, v96, v97
	v_add_f32_e32 v48, v98, v48
	v_add_f32_e32 v48, v99, v48
	v_add_f32_e32 v48, v100, v48
	v_add_f32_e32 v48, v101, v48
	v_cvt_pk_bf16_f32 v154, v96, v97
	v_cvt_pk_bf16_f32 v155, v98, v99
	s_waitcnt lgkmcnt(9)
	v_mfma_f32_32x32x16_bf16 v[112:127], v[60:63], v[158:161], v[32:47]
	ds_read_b64_tr_b16 v[96:97], v175 offset:28672
	ds_read_b64_tr_b16 v[98:99], v175 offset:29184
	v_add_f32_e32 v48, v102, v48
	v_add_f32_e32 v48, v103, v48
	v_add_f32_e32 v48, v104, v48
	v_add_f32_e32 v130, v105, v48
	s_waitcnt lgkmcnt(10)
	v_mfma_f32_32x32x16_bf16 v[48:63], v[162:165], v[158:161], v[32:47]
	v_cvt_pk_bf16_f32 v156, v100, v101
	v_cvt_pk_bf16_f32 v157, v102, v103
	ds_read_b64_tr_b16 v[100:101], v175 offset:25600
	ds_read_b64_tr_b16 v[102:103], v175 offset:26112
	s_waitcnt lgkmcnt(11)
	v_mfma_f32_32x32x16_bf16 v[112:127], v[68:71], v[150:153], v[112:127]
	v_add_f32_e32 v68, v106, v130
	v_add_f32_e32 v68, v107, v68
	v_add_f32_e32 v68, v108, v68
	v_add_f32_e32 v130, v109, v68
	v_cvt_pk_bf16_f32 v146, v104, v105
	v_cvt_pk_bf16_f32 v147, v106, v107
	ds_read_b64_tr_b16 v[68:69], v175 offset:29696
	ds_read_b64_tr_b16 v[70:71], v175 offset:30208
	s_waitcnt lgkmcnt(12)
	v_mfma_f32_32x32x16_bf16 v[48:63], v[166:169], v[150:153], v[48:63]
	v_add_f32_e32 v104, v110, v130
	v_add_f32_e32 v104, v111, v104
	v_add_f32_e32 v104, v80, v104
	v_add_f32_e32 v130, v81, v104
	v_cvt_pk_bf16_f32 v148, v108, v109
	v_cvt_pk_bf16_f32 v149, v110, v111
	ds_read_b64_tr_b16 v[104:105], v175 offset:26624
	ds_read_b64_tr_b16 v[106:107], v175 offset:27136
	s_waitcnt lgkmcnt(13)
	v_mfma_f32_32x32x16_bf16 v[112:127], v[72:75], v[142:145], v[112:127]
	v_add_f32_e32 v72, v82, v130
	v_add_f32_e32 v72, v83, v72
	v_add_f32_e32 v72, v84, v72
	v_add_f32_e32 v108, v85, v72
	v_cvt_pk_bf16_f32 v138, v80, v81
	v_cvt_pk_bf16_f32 v139, v82, v83
	ds_read_b64_tr_b16 v[72:73], v175 offset:30720
	ds_read_b64_tr_b16 v[74:75], v175 offset:31232
	s_waitcnt lgkmcnt(14)
	v_mfma_f32_32x32x16_bf16 v[48:63], v[170:173], v[142:145], v[48:63]
	v_add_f32_e32 v80, v86, v108
	v_add_f32_e32 v80, v87, v80
	v_add_f32_e32 v80, v88, v80
	v_add_f32_e32 v80, v89, v80
	v_cvt_pk_bf16_f32 v140, v84, v85
	v_cvt_pk_bf16_f32 v141, v86, v87
	ds_read_b64_tr_b16 v[84:85], v175 offset:27648
	ds_read_b64_tr_b16 v[86:87], v175 offset:28160
	s_waitcnt lgkmcnt(14)
	v_mfma_f32_32x32x16_bf16 v[112:127], v[76:79], v[134:137], v[112:127]
	v_add_f32_e32 v76, v90, v80
	v_add_f32_e32 v76, v91, v76
	v_add_f32_e32 v76, v92, v76
	v_add_f32_e32 v80, v93, v76
	v_cvt_pk_bf16_f32 v130, v88, v89
	v_cvt_pk_bf16_f32 v131, v90, v91
	ds_read_b64_tr_b16 v[76:77], v175 offset:31744
	ds_read_b64_tr_b16 v[78:79], v175 offset:32256
	v_mfma_f32_32x32x16_bf16 v[48:63], v[64:67], v[134:137], v[48:63]
	v_add_f32_e32 v64, v94, v80
	v_add_f32_e32 v64, v95, v64
	v_add_f32_e32 v64, 0, v64
	v_cvt_pk_bf16_f32 v132, v92, v93
	v_cvt_pk_bf16_f32 v133, v94, v95
	s_mov_b64 s[48:49], 0x3fc000
	v_add_f32_e32 v174, v174, v64
	s_add_i32 s5, s29, s5
	v_lshl_add_u64 v[64:65], v[188:189], 0, s[48:49]
	s_mov_b32 s21, m0
	s_mov_b32 m0, s5
	s_nop 0
	global_load_lds_dwordx4 v[64:65], off
	s_mov_b32 m0, s21
	s_mov_b64 s[30:31], 0x3f4000
	s_add_i32 s5, s20, s4
	v_lshl_add_u64 v[64:65], v[186:187], 0, s[30:31]
	s_mov_b32 s21, m0
	s_mov_b32 m0, s5
	s_nop 0
	global_load_lds_dwordx4 v[64:65], off
	s_mov_b32 m0, s21
	s_waitcnt lgkmcnt(14)
	v_mfma_f32_32x32x16_bf16 v[0:15], v[154:157], v[190:193], v[0:15]
	v_exp_f32_e32 v112, v112
	v_exp_f32_e32 v113, v113
	v_exp_f32_e32 v114, v114
	v_exp_f32_e32 v115, v115
	s_waitcnt lgkmcnt(12)
	v_mfma_f32_32x32x16_bf16 v[16:31], v[154:157], v[96:99], v[16:31]
	v_exp_f32_e32 v116, v116
	v_exp_f32_e32 v117, v117
	v_exp_f32_e32 v118, v118
	v_exp_f32_e32 v119, v119
	v_add_u32_e32 v80, s20, v200
	ds_read_b128 v[64:67], v80
	ds_read_b128 v[88:91], v80 offset:512
	s_waitcnt lgkmcnt(12)
	v_mfma_f32_32x32x16_bf16 v[0:15], v[146:149], v[100:103], v[0:15]
	v_exp_f32_e32 v120, v120
	v_exp_f32_e32 v121, v121
	v_exp_f32_e32 v122, v122
	v_exp_f32_e32 v123, v123
	ds_read_b128 v[92:95], v80 offset:2048
	ds_read_b128 v[162:165], v80 offset:2560
	s_waitcnt lgkmcnt(12)
	v_mfma_f32_32x32x16_bf16 v[16:31], v[146:149], v[68:71], v[16:31]
	v_exp_f32_e32 v124, v124
	v_exp_f32_e32 v125, v125
	v_exp_f32_e32 v126, v126
	v_exp_f32_e32 v127, v127
	ds_read_b128 v[166:169], v80 offset:4096
	ds_read_b128 v[170:173], v80 offset:4608
	s_waitcnt lgkmcnt(12)
	v_mfma_f32_32x32x16_bf16 v[0:15], v[138:141], v[104:107], v[0:15]
	v_exp_f32_e32 v48, v48
	v_exp_f32_e32 v49, v49
	v_exp_f32_e32 v50, v50
	v_exp_f32_e32 v51, v51
	ds_read_b128 v[188:191], v80 offset:6144
	ds_read_b128 v[80:83], v80 offset:6656
	s_waitcnt lgkmcnt(12)
	v_mfma_f32_32x32x16_bf16 v[16:31], v[138:141], v[72:75], v[16:31]
	v_exp_f32_e32 v52, v52
	v_exp_f32_e32 v53, v53
	v_exp_f32_e32 v54, v54
	v_exp_f32_e32 v55, v55
	s_waitcnt lgkmcnt(10)
	v_mfma_f32_32x32x16_bf16 v[0:15], v[130:133], v[84:87], v[0:15]
	v_exp_f32_e32 v56, v56
	v_exp_f32_e32 v57, v57
	v_exp_f32_e32 v58, v58
	v_exp_f32_e32 v59, v59
	s_waitcnt lgkmcnt(8)
	v_mfma_f32_32x32x16_bf16 v[16:31], v[130:133], v[76:79], v[16:31]
	v_exp_f32_e32 v60, v60
	v_exp_f32_e32 v61, v61
	v_exp_f32_e32 v62, v62
	v_exp_f32_e32 v63, v63
	s_waitcnt vmcnt(2) lgkmcnt(0)
	s_barrier
;   #define RESC() do{}while(0)
;   #define ROT() do{sl_prev=sl_cur;sl_cur=sl_next;sl_next=(sl_next==(NSLOT-1)*SLOTB)?0:sl_next+SLOTB;}while(0)
;   #define ENDW(tt) do{ if((tt)+3<NT){WAIT_BAR(2);} else if((tt)+2<NT){WAIT_BAR(1);} else {WAIT_BAR(0);} }while(0)
; template<int THRL> __device__ __forceinline__ void attn_unit(int b,int h,int qb,const bf16*Q,const bf16*__restrict__ K,const bf16*__restrict__ V,bf16*O,float*gssrow,float mref,char*shm){
;     ...
;   for(;t+1<NT;t+=2){
;     STEP(pB0,pB1,pA0,pA1,t,(t+3<NT),(t+1<NT),(t+1<NT));       ENDW(t);   RESC(); ROT();
;     STEP(pA0,pA1,pB0,pB1,t+1,(t+4<NT),(t+2<NT),(t+2<NT));     ENDW(t+1); RESC(); ROT();
;   }
	s_add_i32 s5, s20, 0x2000
	s_cmpk_lg_i32 s20, 0x4000
	s_cselect_b32 s21, s5, 0
	v_add_u32_e32 v175, s29, v199
	ds_read_b64_tr_b16 v[84:85], v175 offset:24576
	ds_read_b64_tr_b16 v[86:87], v175 offset:25088
	v_add_f32_e32 v68, v112, v113
	v_add_f32_e32 v68, v114, v68
	v_add_f32_e32 v68, v115, v68
	v_add_f32_e32 v68, v116, v68
	v_add_f32_e32 v68, v117, v68
	v_cvt_pk_bf16_f32 v154, v112, v113
	v_cvt_pk_bf16_f32 v155, v114, v115
	s_waitcnt lgkmcnt(9)
	v_mfma_f32_32x32x16_bf16 v[96:111], v[64:67], v[158:161], v[32:47]
	ds_read_b64_tr_b16 v[112:113], v175 offset:28672
	ds_read_b64_tr_b16 v[114:115], v175 offset:29184
	v_add_f32_e32 v64, v118, v68
	v_add_f32_e32 v64, v119, v64
	v_add_f32_e32 v64, v120, v64
	v_add_f32_e32 v130, v121, v64
	v_cvt_pk_bf16_f32 v156, v116, v117
	v_cvt_pk_bf16_f32 v157, v118, v119
	s_waitcnt lgkmcnt(10)
	v_mfma_f32_32x32x16_bf16 v[64:79], v[88:91], v[158:161], v[32:47]
	ds_read_b64_tr_b16 v[88:89], v175 offset:25600
	ds_read_b64_tr_b16 v[90:91], v175 offset:26112
	s_waitcnt lgkmcnt(11)
	v_mfma_f32_32x32x16_bf16 v[96:111], v[92:95], v[150:153], v[96:111]
	v_add_f32_e32 v92, v122, v130
	v_add_f32_e32 v92, v123, v92
	v_add_f32_e32 v92, v124, v92
	v_add_f32_e32 v116, v125, v92
	v_cvt_pk_bf16_f32 v146, v120, v121
	v_cvt_pk_bf16_f32 v147, v122, v123
	ds_read_b64_tr_b16 v[92:93], v175 offset:29696
	ds_read_b64_tr_b16 v[94:95], v175 offset:30208
	v_add_f32_e32 v116, v126, v116
	v_add_f32_e32 v116, v127, v116
	v_add_f32_e32 v116, v48, v116
	v_add_f32_e32 v120, v49, v116
	v_cvt_pk_bf16_f32 v148, v124, v125
	v_cvt_pk_bf16_f32 v149, v126, v127
	s_waitcnt lgkmcnt(12)
	v_mfma_f32_32x32x16_bf16 v[64:79], v[162:165], v[150:153], v[64:79]
	ds_read_b64_tr_b16 v[116:117], v175 offset:26624
	ds_read_b64_tr_b16 v[118:119], v175 offset:27136
	v_add_f32_e32 v120, v50, v120
	v_add_f32_e32 v120, v51, v120
	v_add_f32_e32 v120, v52, v120
	v_add_f32_e32 v120, v53, v120
	v_cvt_pk_bf16_f32 v138, v48, v49
	v_cvt_pk_bf16_f32 v139, v50, v51
	s_waitcnt lgkmcnt(13)
	v_mfma_f32_32x32x16_bf16 v[96:111], v[166:169], v[142:145], v[96:111]
	ds_read_b64_tr_b16 v[48:49], v175 offset:30720
	ds_read_b64_tr_b16 v[50:51], v175 offset:31232
	v_add_f32_e32 v120, v54, v120
	v_add_f32_e32 v120, v55, v120
	v_add_f32_e32 v120, v56, v120
	v_add_f32_e32 v120, v57, v120
	v_cvt_pk_bf16_f32 v140, v52, v53
	v_cvt_pk_bf16_f32 v141, v54, v55
	s_waitcnt lgkmcnt(14)
	v_mfma_f32_32x32x16_bf16 v[64:79], v[170:173], v[142:145], v[64:79]
	ds_read_b64_tr_b16 v[52:53], v175 offset:27648
	ds_read_b64_tr_b16 v[54:55], v175 offset:28160
	v_add_f32_e32 v120, v58, v120
	v_add_f32_e32 v120, v59, v120
	v_add_f32_e32 v120, v60, v120
	v_add_f32_e32 v120, v61, v120
	v_cvt_pk_bf16_f32 v130, v56, v57
	v_cvt_pk_bf16_f32 v131, v58, v59
	s_waitcnt lgkmcnt(14)
	v_mfma_f32_32x32x16_bf16 v[96:111], v[188:191], v[134:137], v[96:111]
	ds_read_b64_tr_b16 v[56:57], v175 offset:31744
	ds_read_b64_tr_b16 v[58:59], v175 offset:32256
	v_mfma_f32_32x32x16_bf16 v[64:79], v[80:83], v[134:137], v[64:79]
	v_add_f32_e32 v80, v62, v120
	v_add_f32_e32 v80, v63, v80
	v_add_f32_e32 v80, 0, v80
	v_cvt_pk_bf16_f32 v132, v60, v61
	v_cvt_pk_bf16_f32 v133, v62, v63
	v_lshl_add_u64 v[60:61], v[186:187], 0, s[12:13]
	s_add_i32 s5, s21, s4
	s_mov_b32 s29, m0
	s_mov_b32 m0, s5
	s_nop 0
	global_load_lds_dwordx4 v[60:61], off
	s_mov_b32 m0, s29
	v_add_f32_e32 v174, v174, v80
	s_waitcnt lgkmcnt(14)
	v_mfma_f32_32x32x16_bf16 v[0:15], v[154:157], v[84:87], v[0:15]
	v_exp_f32_e32 v96, v96
	v_exp_f32_e32 v97, v97
	v_exp_f32_e32 v98, v98
	v_exp_f32_e32 v99, v99
	s_waitcnt lgkmcnt(12)
	v_mfma_f32_32x32x16_bf16 v[16:31], v[154:157], v[112:115], v[16:31]
	v_exp_f32_e32 v100, v100
	v_exp_f32_e32 v101, v101
	v_exp_f32_e32 v102, v102
	v_exp_f32_e32 v103, v103
	v_add_u32_e32 v80, s21, v200
	ds_read_b128 v[60:63], v80
	ds_read_b128 v[120:123], v80 offset:512
	s_waitcnt lgkmcnt(12)
	v_mfma_f32_32x32x16_bf16 v[0:15], v[146:149], v[88:91], v[0:15]
	v_exp_f32_e32 v104, v104
	v_exp_f32_e32 v105, v105
	v_exp_f32_e32 v106, v106
	v_exp_f32_e32 v107, v107
	ds_read_b128 v[124:127], v80 offset:2048
	ds_read_b128 v[162:165], v80 offset:2560
	s_waitcnt lgkmcnt(12)
	v_mfma_f32_32x32x16_bf16 v[16:31], v[146:149], v[92:95], v[16:31]
	v_exp_f32_e32 v108, v108
	v_exp_f32_e32 v109, v109
	v_exp_f32_e32 v110, v110
	v_exp_f32_e32 v111, v111
	ds_read_b128 v[166:169], v80 offset:4096
	ds_read_b128 v[170:173], v80 offset:4608
	s_waitcnt lgkmcnt(12)
	v_mfma_f32_32x32x16_bf16 v[0:15], v[138:141], v[116:119], v[0:15]
	v_exp_f32_e32 v64, v64
	v_exp_f32_e32 v65, v65
	v_exp_f32_e32 v66, v66
	v_exp_f32_e32 v67, v67
	ds_read_b128 v[116:119], v80 offset:6144
	ds_read_b128 v[112:115], v80 offset:6656
	s_waitcnt lgkmcnt(12)
	v_mfma_f32_32x32x16_bf16 v[16:31], v[138:141], v[48:51], v[16:31]
	v_exp_f32_e32 v68, v68
	v_exp_f32_e32 v69, v69
	v_exp_f32_e32 v70, v70
	v_exp_f32_e32 v71, v71
	s_waitcnt lgkmcnt(10)
	v_mfma_f32_32x32x16_bf16 v[0:15], v[130:133], v[52:55], v[0:15]
	v_exp_f32_e32 v72, v72
	v_exp_f32_e32 v73, v73
	v_exp_f32_e32 v74, v74
	v_exp_f32_e32 v75, v75
	s_waitcnt lgkmcnt(8)
	v_mfma_f32_32x32x16_bf16 v[16:31], v[130:133], v[56:59], v[16:31]
	v_exp_f32_e32 v76, v76
	v_exp_f32_e32 v77, v77
	v_exp_f32_e32 v78, v78
	v_exp_f32_e32 v79, v79
	s_waitcnt vmcnt(1) lgkmcnt(0)
	s_barrier
;   #define RESC() do{}while(0)
;   #define ROT() do{sl_prev=sl_cur;sl_cur=sl_next;sl_next=(sl_next==(NSLOT-1)*SLOTB)?0:sl_next+SLOTB;}while(0)
;   #define ENDW(tt) do{ if((tt)+3<NT){WAIT_BAR(2);} else if((tt)+2<NT){WAIT_BAR(1);} else {WAIT_BAR(0);} }while(0)
; template<int THRL> __device__ __forceinline__ void attn_unit(int b,int h,int qb,const bf16*Q,const bf16*__restrict__ K,const bf16*__restrict__ V,bf16*O,float*gssrow,float mref,char*shm){
;     ...
;   for(;t+1<NT;t+=2){
;     STEP(pB0,pB1,pA0,pA1,t,(t+3<NT),(t+1<NT),(t+1<NT));       ENDW(t);   RESC(); ROT();
;     STEP(pA0,pA1,pB0,pB1,t+1,(t+4<NT),(t+2<NT),(t+2<NT));     ENDW(t+1); RESC(); ROT();
;   }
	s_add_i32 s5, s21, 0x2000
	s_cmpk_lg_i32 s21, 0x4000
	s_cselect_b32 s5, s5, 0
	v_add_u32_e32 v175, s20, v199
	ds_read_b64_tr_b16 v[188:189], v175 offset:24576
	ds_read_b64_tr_b16 v[190:191], v175 offset:25088
	v_add_f32_e32 v48, v96, v97
	v_add_f32_e32 v48, v98, v48
	v_add_f32_e32 v48, v99, v48
	v_add_f32_e32 v48, v100, v48
	v_add_f32_e32 v48, v101, v48
	v_cvt_pk_bf16_f32 v154, v96, v97
	v_cvt_pk_bf16_f32 v155, v98, v99
	s_waitcnt lgkmcnt(9)
	v_mfma_f32_32x32x16_bf16 v[80:95], v[60:63], v[158:161], v[32:47]
	ds_read_b64_tr_b16 v[96:97], v175 offset:28672
	ds_read_b64_tr_b16 v[98:99], v175 offset:29184
	v_add_f32_e32 v48, v102, v48
	v_add_f32_e32 v48, v103, v48
	v_add_f32_e32 v48, v104, v48
	v_add_f32_e32 v130, v105, v48
	s_waitcnt lgkmcnt(10)
	v_mfma_f32_32x32x16_bf16 v[48:63], v[120:123], v[158:161], v[32:47]
	v_cvt_pk_bf16_f32 v156, v100, v101
	v_cvt_pk_bf16_f32 v157, v102, v103
	ds_read_b64_tr_b16 v[120:121], v175 offset:25600
	ds_read_b64_tr_b16 v[122:123], v175 offset:26112
	v_add_f32_e32 v100, v106, v130
	v_add_f32_e32 v100, v107, v100
	v_add_f32_e32 v100, v108, v100
	v_add_f32_e32 v100, v109, v100
	v_cvt_pk_bf16_f32 v146, v104, v105
	v_cvt_pk_bf16_f32 v147, v106, v107
	s_waitcnt lgkmcnt(11)
	v_mfma_f32_32x32x16_bf16 v[80:95], v[124:127], v[150:153], v[80:95]
	ds_read_b64_tr_b16 v[102:103], v175 offset:29696
	ds_read_b64_tr_b16 v[104:105], v175 offset:30208
	s_waitcnt lgkmcnt(12)
	v_mfma_f32_32x32x16_bf16 v[48:63], v[162:165], v[150:153], v[48:63]
	v_add_f32_e32 v100, v110, v100
	v_add_f32_e32 v100, v111, v100
	v_add_f32_e32 v100, v64, v100
	v_add_f32_e32 v100, v65, v100
	v_cvt_pk_bf16_f32 v148, v108, v109
	v_cvt_pk_bf16_f32 v149, v110, v111
	ds_read_b64_tr_b16 v[106:107], v175 offset:26624
	ds_read_b64_tr_b16 v[108:109], v175 offset:27136
	v_add_f32_e32 v100, v66, v100
	v_add_f32_e32 v100, v67, v100
	v_add_f32_e32 v100, v68, v100
	v_add_f32_e32 v100, v69, v100
	v_cvt_pk_bf16_f32 v138, v64, v65
	v_cvt_pk_bf16_f32 v139, v66, v67
	s_waitcnt lgkmcnt(13)
	v_mfma_f32_32x32x16_bf16 v[80:95], v[166:169], v[142:145], v[80:95]
	ds_read_b64_tr_b16 v[64:65], v175 offset:30720
	ds_read_b64_tr_b16 v[66:67], v175 offset:31232
	s_waitcnt lgkmcnt(14)
	v_mfma_f32_32x32x16_bf16 v[48:63], v[170:173], v[142:145], v[48:63]
	v_add_f32_e32 v100, v70, v100
	v_add_f32_e32 v100, v71, v100
	v_add_f32_e32 v100, v72, v100
	v_add_f32_e32 v100, v73, v100
	v_cvt_pk_bf16_f32 v140, v68, v69
	v_cvt_pk_bf16_f32 v141, v70, v71
	ds_read_b64_tr_b16 v[68:69], v175 offset:27648
	ds_read_b64_tr_b16 v[70:71], v175 offset:28160
	v_add_f32_e32 v100, v74, v100
	v_add_f32_e32 v100, v75, v100
	v_add_f32_e32 v100, v76, v100
	v_add_f32_e32 v100, v77, v100
	v_cvt_pk_bf16_f32 v130, v72, v73
	v_cvt_pk_bf16_f32 v131, v74, v75
	s_waitcnt lgkmcnt(14)
	v_mfma_f32_32x32x16_bf16 v[80:95], v[116:119], v[134:137], v[80:95]
	ds_read_b64_tr_b16 v[72:73], v175 offset:31744
	ds_read_b64_tr_b16 v[74:75], v175 offset:32256
	v_mfma_f32_32x32x16_bf16 v[48:63], v[112:115], v[134:137], v[48:63]
	v_add_f32_e32 v100, v78, v100
	v_add_f32_e32 v100, v79, v100
	v_add_f32_e32 v100, 0, v100
	v_cvt_pk_bf16_f32 v132, v76, v77
	v_cvt_pk_bf16_f32 v133, v78, v79
	s_add_i32 s4, s5, s4
	v_lshl_add_u64 v[76:77], v[186:187], 0, s[48:49]
	s_mov_b32 s20, m0
	s_mov_b32 m0, s4
	s_nop 0
	global_load_lds_dwordx4 v[76:77], off
	s_mov_b32 m0, s20
	v_add_f32_e32 v100, v174, v100
	s_waitcnt lgkmcnt(14)
	v_mfma_f32_32x32x16_bf16 v[0:15], v[154:157], v[188:191], v[0:15]
	v_exp_f32_e32 v80, v80
	v_exp_f32_e32 v81, v81
	v_exp_f32_e32 v82, v82
	v_exp_f32_e32 v83, v83
	s_waitcnt lgkmcnt(12)
	v_mfma_f32_32x32x16_bf16 v[16:31], v[154:157], v[96:99], v[16:31]
	v_exp_f32_e32 v84, v84
	v_exp_f32_e32 v85, v85
	v_exp_f32_e32 v86, v86
	v_exp_f32_e32 v87, v87
	v_add_u32_e32 v76, s5, v200
	ds_read_b128 v[110:113], v76
	ds_read_b128 v[114:117], v76 offset:512
	s_waitcnt lgkmcnt(12)
	v_mfma_f32_32x32x16_bf16 v[0:15], v[146:149], v[120:123], v[0:15]
	v_exp_f32_e32 v88, v88
	v_exp_f32_e32 v89, v89
	v_exp_f32_e32 v90, v90
	v_exp_f32_e32 v91, v91
	ds_read_b128 v[118:121], v76 offset:2048
	ds_read_b128 v[122:125], v76 offset:2560
	s_waitcnt lgkmcnt(12)
	v_mfma_f32_32x32x16_bf16 v[16:31], v[146:149], v[102:105], v[16:31]
	v_exp_f32_e32 v92, v92
	v_exp_f32_e32 v93, v93
	v_exp_f32_e32 v94, v94
	v_exp_f32_e32 v95, v95
	ds_read_b128 v[102:105], v76 offset:4096
	ds_read_b128 v[162:165], v76 offset:4608
	s_waitcnt lgkmcnt(12)
	v_mfma_f32_32x32x16_bf16 v[0:15], v[138:141], v[106:109], v[0:15]
	v_exp_f32_e32 v48, v48
	v_exp_f32_e32 v49, v49
	v_exp_f32_e32 v50, v50
	v_exp_f32_e32 v51, v51
	ds_read_b128 v[106:109], v76 offset:6144
	ds_read_b128 v[96:99], v76 offset:6656
	s_waitcnt lgkmcnt(12)
	v_mfma_f32_32x32x16_bf16 v[16:31], v[138:141], v[64:67], v[16:31]
	v_exp_f32_e32 v52, v52
	v_exp_f32_e32 v53, v53
	v_exp_f32_e32 v54, v54
	v_exp_f32_e32 v55, v55
	s_waitcnt lgkmcnt(10)
	v_mfma_f32_32x32x16_bf16 v[0:15], v[130:133], v[68:71], v[0:15]
	v_exp_f32_e32 v56, v56
	v_exp_f32_e32 v57, v57
	v_exp_f32_e32 v58, v58
	v_exp_f32_e32 v59, v59
	s_waitcnt lgkmcnt(8)
	v_mfma_f32_32x32x16_bf16 v[16:31], v[130:133], v[72:75], v[16:31]
	v_exp_f32_e32 v60, v60
	v_exp_f32_e32 v61, v61
	v_exp_f32_e32 v62, v62
	v_exp_f32_e32 v63, v63
	s_waitcnt vmcnt(0) lgkmcnt(0)
	s_barrier
; #define SBAR() __builtin_amdgcn_sched_barrier(0)
;   #define RESC() do{}while(0)
;   #define PKW(P,B) cvtpk_s(P[B],P[B+1])
; __device__ __forceinline__ void pv(f32x16*o,int vb,bf16x8 pa0,bf16x8 pa1,bf16x8 pa2,bf16x8 pa3){
;   #pragma unroll
;   for(int d0=0;d0<2;++d0){s16x4 lo[4],hi[4];
;     #pragma unroll
;     for(int ks=0;ks<4;++ks){
;       asm volatile("ds_read_b64_tr_b16 %0,%1 offset:%c2":"=&v"(lo[ks]):"v"(vb),"i"(d0*4096+ks*1024):"memory");
;       asm volatile("ds_read_b64_tr_b16 %0,%1 offset:%c2":"=&v"(hi[ks]):"v"(vb),"i"(d0*4096+ks*1024+512):"memory");}
;     asm volatile("s_waitcnt lgkmcnt(0)":::"memory");SBAR();
; template<int THRL> __device__ __forceinline__ void attn_unit(int b,int h,int qb,const bf16*Q,const bf16*__restrict__ K,const bf16*__restrict__ V,bf16*O,float*gssrow,float mref,char*shm){
;     ...
;   STEP(pB0,pB1,pA0,pA1,NT-1,false,false,false); RESC();
;   { float sacc=pB0[0]+pB0[1]; _Pragma("unroll") for(int r=2;r<16;++r)sacc+=pB0[r]; _Pragma("unroll") for(int r=0;r<16;++r)sacc+=pB1[r]; l_reg+=sacc;
;     pw0=(u32x4){PKW(pB0,0),PKW(pB0,2),PKW(pB0,4),PKW(pB0,6)};pw1=(u32x4){PKW(pB0,8),PKW(pB0,10),PKW(pB0,12),PKW(pB0,14)};pw2=(u32x4){PKW(pB1,0),PKW(pB1,2),PKW(pB1,4),PKW(pB1,6)};pw3=(u32x4){PKW(pB1,8),PKW(pB1,10),PKW(pB1,12),PKW(pB1,14)};
;     SBAR(); pv(o,vb0+sl_cur,PAF(0),PAF(1),PAF(2),PAF(3)); }
	v_add_u32_e32 v101, s21, v199
	ds_read_b64_tr_b16 v[166:167], v101 offset:24576
	ds_read_b64_tr_b16 v[168:169], v101 offset:25088
	v_add_f32_e32 v64, v80, v81
	v_add_f32_e32 v64, v82, v64
	v_add_f32_e32 v64, v83, v64
	v_add_f32_e32 v64, v84, v64
	v_add_f32_e32 v126, v85, v64
	v_cvt_pk_bf16_f32 v154, v80, v81
	v_cvt_pk_bf16_f32 v155, v82, v83
	s_waitcnt lgkmcnt(9)
	v_mfma_f32_32x32x16_bf16 v[64:79], v[110:113], v[158:161], v[32:47]
	ds_read_b64_tr_b16 v[80:81], v101 offset:28672
	ds_read_b64_tr_b16 v[82:83], v101 offset:29184
	s_waitcnt lgkmcnt(10)
	v_mfma_f32_32x32x16_bf16 v[32:47], v[114:117], v[158:161], v[32:47]
	v_add_f32_e32 v110, v86, v126
	v_add_f32_e32 v110, v87, v110
	v_add_f32_e32 v110, v88, v110
	v_add_f32_e32 v110, v89, v110
	v_cvt_pk_bf16_f32 v156, v84, v85
	v_cvt_pk_bf16_f32 v157, v86, v87
	ds_read_b64_tr_b16 v[84:85], v101 offset:25600
	ds_read_b64_tr_b16 v[86:87], v101 offset:26112
	v_add_f32_e32 v110, v90, v110
	v_add_f32_e32 v110, v91, v110
	v_add_f32_e32 v110, v92, v110
	v_add_f32_e32 v110, v93, v110
	v_cvt_pk_bf16_f32 v146, v88, v89
	v_cvt_pk_bf16_f32 v147, v90, v91
	s_waitcnt lgkmcnt(11)
	v_mfma_f32_32x32x16_bf16 v[64:79], v[118:121], v[150:153], v[64:79]
	ds_read_b64_tr_b16 v[88:89], v101 offset:29696
	ds_read_b64_tr_b16 v[90:91], v101 offset:30208
	s_waitcnt lgkmcnt(12)
	v_mfma_f32_32x32x16_bf16 v[32:47], v[122:125], v[150:153], v[32:47]
	v_add_f32_e32 v110, v94, v110
	v_add_f32_e32 v110, v95, v110
	v_add_f32_e32 v110, v48, v110
	v_add_f32_e32 v110, v49, v110
	v_cvt_pk_bf16_f32 v148, v92, v93
	v_cvt_pk_bf16_f32 v149, v94, v95
	ds_read_b64_tr_b16 v[92:93], v101 offset:26624
	ds_read_b64_tr_b16 v[94:95], v101 offset:27136
	s_waitcnt lgkmcnt(13)
	v_mfma_f32_32x32x16_bf16 v[64:79], v[102:105], v[142:145], v[64:79]
	v_add_f32_e32 v102, v50, v110
	v_add_f32_e32 v102, v51, v102
	v_add_f32_e32 v102, v52, v102
	v_add_f32_e32 v102, v53, v102
	v_cvt_pk_bf16_f32 v138, v48, v49
	v_cvt_pk_bf16_f32 v139, v50, v51
	ds_read_b64_tr_b16 v[48:49], v101 offset:30720
	ds_read_b64_tr_b16 v[50:51], v101 offset:31232
	s_waitcnt lgkmcnt(14)
	v_mfma_f32_32x32x16_bf16 v[32:47], v[162:165], v[142:145], v[32:47]
	v_add_f32_e32 v102, v54, v102
	v_add_f32_e32 v102, v55, v102
	v_add_f32_e32 v102, v56, v102
	v_add_f32_e32 v102, v57, v102
	v_cvt_pk_bf16_f32 v140, v52, v53
	v_cvt_pk_bf16_f32 v141, v54, v55
	ds_read_b64_tr_b16 v[52:53], v101 offset:27648
	ds_read_b64_tr_b16 v[54:55], v101 offset:28160
	v_add_f32_e32 v102, v58, v102
	v_add_f32_e32 v102, v59, v102
	v_add_f32_e32 v102, v60, v102
	v_add_f32_e32 v102, v61, v102
	v_cvt_pk_bf16_f32 v130, v56, v57
	v_cvt_pk_bf16_f32 v131, v58, v59
	s_waitcnt lgkmcnt(14)
	v_mfma_f32_32x32x16_bf16 v[64:79], v[106:109], v[134:137], v[64:79]
	ds_read_b64_tr_b16 v[56:57], v101 offset:31744
	ds_read_b64_tr_b16 v[58:59], v101 offset:32256
	v_mfma_f32_32x32x16_bf16 v[32:47], v[96:99], v[134:137], v[32:47]
	v_add_f32_e32 v96, v62, v102
	v_add_f32_e32 v96, v63, v96
	v_add_f32_e32 v96, 0, v96
	v_cvt_pk_bf16_f32 v132, v60, v61
	v_cvt_pk_bf16_f32 v133, v62, v63
	s_waitcnt lgkmcnt(14)
	v_mfma_f32_32x32x16_bf16 v[0:15], v[154:157], v[166:169], v[0:15]
	s_nop 1
	v_exp_f32_e32 v64, v64
	v_exp_f32_e32 v65, v65
	v_exp_f32_e32 v66, v66
	v_exp_f32_e32 v67, v67
	s_waitcnt lgkmcnt(12)
	v_mfma_f32_32x32x16_bf16 v[16:31], v[154:157], v[80:83], v[16:31]
	v_exp_f32_e32 v68, v68
	v_exp_f32_e32 v69, v69
	v_exp_f32_e32 v70, v70
	v_exp_f32_e32 v71, v71
	s_waitcnt lgkmcnt(10)
	v_mfma_f32_32x32x16_bf16 v[0:15], v[146:149], v[84:87], v[0:15]
	v_exp_f32_e32 v72, v72
	v_exp_f32_e32 v73, v73
	v_exp_f32_e32 v74, v74
	v_exp_f32_e32 v75, v75
	s_waitcnt lgkmcnt(8)
	v_mfma_f32_32x32x16_bf16 v[16:31], v[146:149], v[88:91], v[16:31]
	v_exp_f32_e32 v76, v76
	v_exp_f32_e32 v77, v77
	v_exp_f32_e32 v78, v78
	v_exp_f32_e32 v79, v79
	s_waitcnt lgkmcnt(6)
	v_mfma_f32_32x32x16_bf16 v[0:15], v[138:141], v[92:95], v[0:15]
	v_exp_f32_e32 v32, v32
	v_exp_f32_e32 v33, v33
	v_exp_f32_e32 v34, v34
	v_exp_f32_e32 v35, v35
	s_waitcnt lgkmcnt(4)
	v_mfma_f32_32x32x16_bf16 v[16:31], v[138:141], v[48:51], v[16:31]
	v_exp_f32_e32 v36, v36
	v_exp_f32_e32 v37, v37
	v_exp_f32_e32 v38, v38
	v_exp_f32_e32 v39, v39
	s_waitcnt lgkmcnt(2)
	v_mfma_f32_32x32x16_bf16 v[0:15], v[130:133], v[52:55], v[0:15]
	v_exp_f32_e32 v40, v40
	v_exp_f32_e32 v41, v41
	v_exp_f32_e32 v42, v42
	v_exp_f32_e32 v43, v43
	s_waitcnt lgkmcnt(0)
	v_mfma_f32_32x32x16_bf16 v[16:31], v[130:133], v[56:59], v[16:31]
	v_exp_f32_e32 v44, v44
	v_exp_f32_e32 v45, v45
	v_exp_f32_e32 v46, v46
	v_exp_f32_e32 v47, v47
	v_add_f32_e32 v48, v64, v65
	v_add_f32_e32 v48, v66, v48
	v_add_f32_e32 v48, v67, v48
	v_add_f32_e32 v48, v68, v48
	v_add_f32_e32 v48, v69, v48
	v_add_f32_e32 v48, v70, v48
	v_add_f32_e32 v48, v71, v48
	v_add_f32_e32 v48, v72, v48
	v_add_f32_e32 v48, v73, v48
	v_add_f32_e32 v48, v74, v48
	v_add_f32_e32 v48, v75, v48
	v_add_f32_e32 v48, v76, v48
	v_add_f32_e32 v48, v77, v48
	v_add_f32_e32 v48, v78, v48
	v_add_f32_e32 v48, v79, v48
	v_add_f32_e32 v48, v32, v48
	v_add_f32_e32 v48, v33, v48
	v_add_f32_e32 v48, v34, v48
	v_add_f32_e32 v48, v35, v48
	v_add_f32_e32 v48, v36, v48
	v_add_f32_e32 v48, v37, v48
	v_add_f32_e32 v48, v38, v48
	v_add_f32_e32 v48, v39, v48
	v_add_f32_e32 v48, v40, v48
	v_add_f32_e32 v48, v41, v48
	v_add_f32_e32 v48, v42, v48
	v_add_f32_e32 v48, v43, v48
	v_add_f32_e32 v48, v44, v48
	v_add_f32_e32 v48, v45, v48
	v_add_f32_e32 v48, v46, v48
	v_add_f32_e32 v48, v47, v48
	v_add_f32_e32 v49, v100, v96
	v_add_f32_e32 v48, v49, v48
	v_cvt_pk_bf16_f32 v32, v32, v33
	v_cvt_pk_bf16_f32 v50, v64, v65
	v_cvt_pk_bf16_f32 v51, v66, v67
	v_cvt_pk_bf16_f32 v52, v68, v69
	v_cvt_pk_bf16_f32 v53, v70, v71
	v_cvt_pk_bf16_f32 v54, v72, v73
	v_cvt_pk_bf16_f32 v55, v74, v75
	v_cvt_pk_bf16_f32 v56, v76, v77
	v_cvt_pk_bf16_f32 v57, v78, v79
	v_cvt_pk_bf16_f32 v33, v34, v35
	v_cvt_pk_bf16_f32 v34, v36, v37
	v_cvt_pk_bf16_f32 v35, v38, v39
	v_cvt_pk_bf16_f32 v36, v40, v41
	v_cvt_pk_bf16_f32 v37, v42, v43
	v_cvt_pk_bf16_f32 v38, v44, v45
	v_cvt_pk_bf16_f32 v39, v46, v47
	v_add3_u32 v49, v128, v198, s5
	ds_read_b64_tr_b16 v[40:41],v49 offset:0
	ds_read_b64_tr_b16 v[42:43],v49 offset:512
	ds_read_b64_tr_b16 v[44:45],v49 offset:1024
	ds_read_b64_tr_b16 v[46:47],v49 offset:1536
	ds_read_b64_tr_b16 v[58:59],v49 offset:2048
	ds_read_b64_tr_b16 v[60:61],v49 offset:2560
	ds_read_b64_tr_b16 v[62:63],v49 offset:3072
	ds_read_b64_tr_b16 v[64:65],v49 offset:3584
	s_waitcnt lgkmcnt(0)
; __device__ __forceinline__ int crow(int r,int hi){return (r&3)+8*(r>>2)+4*hi;}
; #define SBAR() __builtin_amdgcn_sched_barrier(0)
; __device__ __forceinline__ void pv(f32x16*o,int vb,bf16x8 pa0,bf16x8 pa1,bf16x8 pa2,bf16x8 pa3){
;   #pragma unroll
;   for(int d0=0;d0<2;++d0){s16x4 lo[4],hi[4];
;     #pragma unroll
;     for(int ks=0;ks<4;++ks){
;       asm volatile("ds_read_b64_tr_b16 %0,%1 offset:%c2":"=&v"(lo[ks]):"v"(vb),"i"(d0*4096+ks*1024):"memory");
;       asm volatile("ds_read_b64_tr_b16 %0,%1 offset:%c2":"=&v"(hi[ks]):"v"(vb),"i"(d0*4096+ks*1024+512):"memory");}
;     asm volatile("s_waitcnt lgkmcnt(0)":::"memory");SBAR();
;     ...
;     o[d0]=__builtin_amdgcn_mfma_f32_32x32x16_bf16(pa0,PK(0),o[d0],0,0,0);
;     o[d0]=__builtin_amdgcn_mfma_f32_32x32x16_bf16(pa1,PK(1),o[d0],0,0,0);
;     o[d0]=__builtin_amdgcn_mfma_f32_32x32x16_bf16(pa2,PK(2),o[d0],0,0,0);
;     o[d0]=__builtin_amdgcn_mfma_f32_32x32x16_bf16(pa3,PK(3),o[d0],0,0,0);
;     ...
;   }
; }
; template<int THRL> __device__ __forceinline__ void attn_unit(int b,int h,int qb,const bf16*Q,const bf16*__restrict__ K,const bf16*__restrict__ V,bf16*O,float*gssrow,float mref,char*shm){
;     ...
;   __builtin_amdgcn_s_setprio(0);
;   {auto rr=__builtin_amdgcn_permlane32_swap(__float_as_uint(l_reg),__float_as_uint(l_reg),false,false);l_reg=__uint_as_float(rr[0])+__uint_as_float(rr[1]);}
;   if(hi==0)wsf[32+r32]=l_reg;asm volatile("s_waitcnt lgkmcnt(0)":::"memory");
;   float rli[16];
;   #pragma unroll
;   for(int r=0;r<16;++r)rli[r]=__builtin_amdgcn_rcpf(wsf[32+crow(r,hi)]);
;   bf16*Ow=O+(rowbase+q0+wid*QBLK)*OP+h*D;
;   { bf16*stg=(bf16*)(shm+LDS_OST)+wid*2048;
;     #pragma unroll
;     for(int r=0;r<16;++r){const int orow=crow(r,hi);
;       #pragma unroll
;       for(int d0=0;d0<2;++d0)stg[orow*64+d0*32+r32]=__float2bfloat16(o[d0][r]*rli[r]);}
	s_nop 0
	v_mfma_f32_32x32x16_bf16 v[0:15], v[50:53], v[40:43], v[0:15]
	ds_read_b64_tr_b16 v[40:41],v49 offset:4096
	ds_read_b64_tr_b16 v[42:43],v49 offset:4608
	v_mfma_f32_32x32x16_bf16 v[0:15], v[54:57], v[44:47], v[0:15]
	ds_read_b64_tr_b16 v[44:45],v49 offset:5120
	ds_read_b64_tr_b16 v[46:47],v49 offset:5632
	v_mfma_f32_32x32x16_bf16 v[0:15], v[32:35], v[58:61], v[0:15]
	ds_read_b64_tr_b16 v[58:59],v49 offset:6144
	ds_read_b64_tr_b16 v[60:61],v49 offset:6656
	v_mfma_f32_32x32x16_bf16 v[0:15], v[36:39], v[62:65], v[0:15]
	ds_read_b64_tr_b16 v[62:63],v49 offset:7168
	ds_read_b64_tr_b16 v[64:65],v49 offset:7680
	s_waitcnt lgkmcnt(0)
	v_mfma_f32_32x32x16_bf16 v[16:31], v[50:53], v[40:43], v[16:31]
	v_mfma_f32_32x32x16_bf16 v[16:31], v[54:57], v[44:47], v[16:31]
	v_mfma_f32_32x32x16_bf16 v[16:31], v[32:35], v[58:61], v[16:31]
	v_mfma_f32_32x32x16_bf16 v[16:31], v[36:39], v[62:65], v[16:31]
	s_setprio 0
	v_mov_b32_e32 v32, v48
	s_nop 1
	v_permlane32_swap_b32_e32 v48, v32
	v_cmp_gt_u32_e32 vcc, 32, v195
	s_and_saveexec_b64 s[4:5], vcc
	v_add_f32_e32 v32, v48, v32
	v_lshl_add_u32 v33, v196, 2, s15
	ds_write_b32 v33, v32 offset:49280
	s_or_b64 exec, exec, s[4:5]
	s_waitcnt lgkmcnt(0)
	v_lshl_add_u32 v40, v197, 4, s15
	ds_read_b128 v[32:35], v40 offset:49280
	ds_read_b128 v[36:39], v40 offset:49312
	s_lshl_b64 s[4:5], s[46:47], 11
	v_readlane_b32 s12, v253, 63
	s_add_u32 s4, s12, s4
	s_waitcnt lgkmcnt(1)
	v_rcp_f32_e32 v41, v32
	v_readlane_b32 s12, v254, 0
	s_addc_u32 s5, s12, s5
	s_lshl_b32 s14, s14, 12
	v_rcp_f32_e32 v42, v33
	v_rcp_f32_e32 v43, v34
	v_rcp_f32_e32 v44, v35
	s_waitcnt lgkmcnt(0)
	v_rcp_f32_e32 v45, v36
	ds_read_b128 v[32:35], v40 offset:49344
	v_rcp_f32_e32 v46, v37
	v_rcp_f32_e32 v47, v38
	v_rcp_f32_e32 v48, v39
	ds_read_b128 v[36:39], v40 offset:49376
	s_add_i32 s14, s14, 0
	v_lshlrev_b32_e32 v40, 9, v197
	v_lshlrev_b32_e32 v49, 1, v196
	v_mul_f32_e32 v0, v0, v41
	v_add3_u32 v40, s14, v40, v49
	v_cvt_pk_bf16_f32 v0, v0, s0
	ds_write_b16 v40, v0 offset:51200
	v_mul_f32_e32 v0, v16, v41
	v_cvt_pk_bf16_f32 v0, v0, s0
	ds_write_b16 v40, v0 offset:51264
	v_mul_f32_e32 v0, v1, v42
	v_cvt_pk_bf16_f32 v0, v0, s0
	ds_write_b16 v40, v0 offset:51328
	v_mul_f32_e32 v0, v17, v42
	v_cvt_pk_bf16_f32 v0, v0, s0
	ds_write_b16 v40, v0 offset:51392
	v_mul_f32_e32 v0, v2, v43
	v_cvt_pk_bf16_f32 v0, v0, s0
	ds_write_b16 v40, v0 offset:51456
	v_mul_f32_e32 v0, v18, v43
	v_cvt_pk_bf16_f32 v0, v0, s0
	ds_write_b16 v40, v0 offset:51520
	v_mul_f32_e32 v0, v3, v44
	v_cvt_pk_bf16_f32 v0, v0, s0
	ds_write_b16 v40, v0 offset:51584
	v_mul_f32_e32 v0, v19, v44
	v_cvt_pk_bf16_f32 v0, v0, s0
	ds_write_b16 v40, v0 offset:51648
	v_mul_f32_e32 v0, v4, v45
	v_cvt_pk_bf16_f32 v0, v0, s0
	ds_write_b16 v40, v0 offset:52224
	v_mul_f32_e32 v0, v20, v45
	v_cvt_pk_bf16_f32 v0, v0, s0
	ds_write_b16 v40, v0 offset:52288
	v_mul_f32_e32 v0, v5, v46
	v_cvt_pk_bf16_f32 v0, v0, s0
	ds_write_b16 v40, v0 offset:52352
	v_mul_f32_e32 v0, v21, v46
	v_cvt_pk_bf16_f32 v0, v0, s0
	ds_write_b16 v40, v0 offset:52416
	v_mul_f32_e32 v0, v6, v47
	v_cvt_pk_bf16_f32 v0, v0, s0
	ds_write_b16 v40, v0 offset:52480
	v_mul_f32_e32 v0, v22, v47
	v_cvt_pk_bf16_f32 v0, v0, s0
	s_waitcnt lgkmcnt(14)
; __device__ __forceinline__ int crow(int r,int hi){return (r&3)+8*(r>>2)+4*hi;}
; template<int THRL> __device__ __forceinline__ void attn_unit(int b,int h,int qb,const bf16*Q,const bf16*__restrict__ K,const bf16*__restrict__ V,bf16*O,float*gssrow,float mref,char*shm){
;     ...
;   { bf16*stg=(bf16*)(shm+LDS_OST)+wid*2048;
;     #pragma unroll
;     for(int r=0;r<16;++r){const int orow=crow(r,hi);
;       #pragma unroll
;       for(int d0=0;d0<2;++d0)stg[orow*64+d0*32+r32]=__float2bfloat16(o[d0][r]*rli[r]);}
;     asm volatile("s_waitcnt lgkmcnt(0)":::"memory");
;     #pragma unroll
;     for(int i=0;i<4;++i){const int row=i*8+(lane>>3),ch=lane&7; const u32x4 v=*(const u32x4*)(stg+row*64+ch*8); ATTN_STORE16(Ow+(long)row*OP+ch*8,v);
;       float ss=0.f;
;       #pragma unroll
;       for(int e=0;e<4;++e){const float lo=__uint_as_float(v[e]<<16),hi_=__uint_as_float(v[e]&0xffff0000u); ss+=lo*lo+hi_*hi_;}
;       ss+=__shfl_xor(ss,1); ss+=__shfl_xor(ss,2); ss+=__shfl_xor(ss,4);
;       if(ch==0)atomicAdd(gssrow+rowbase+q0+wid*QBLK+row,ss);} }
	v_rcp_f32_e32 v32, v32
	ds_write_b16 v40, v0 offset:52544
	v_mul_f32_e32 v0, v7, v48
	v_cvt_pk_bf16_f32 v0, v0, s0
	ds_write_b16 v40, v0 offset:52608
	v_mul_f32_e32 v0, v23, v48
	v_cvt_pk_bf16_f32 v0, v0, s0
	v_rcp_f32_e32 v33, v33
	ds_write_b16 v40, v0 offset:52672
	v_mul_f32_e32 v0, v8, v32
	v_cvt_pk_bf16_f32 v0, v0, s0
	ds_write_b16 v40, v0 offset:53248
	v_mul_f32_e32 v0, v24, v32
	v_cvt_pk_bf16_f32 v0, v0, s0
	v_rcp_f32_e32 v34, v34
	ds_write_b16 v40, v0 offset:53312
	v_mul_f32_e32 v0, v9, v33
	v_cvt_pk_bf16_f32 v0, v0, s0
	ds_write_b16 v40, v0 offset:53376
	v_mul_f32_e32 v0, v25, v33
	v_cvt_pk_bf16_f32 v0, v0, s0
	v_rcp_f32_e32 v35, v35
	ds_write_b16 v40, v0 offset:53440
	v_mul_f32_e32 v0, v10, v34
	v_cvt_pk_bf16_f32 v0, v0, s0
	ds_write_b16 v40, v0 offset:53504
	v_mul_f32_e32 v0, v26, v34
	v_cvt_pk_bf16_f32 v0, v0, s0
	s_waitcnt lgkmcnt(14)
	v_rcp_f32_e32 v36, v36
	ds_write_b16 v40, v0 offset:53568
	v_mul_f32_e32 v0, v11, v35
	v_cvt_pk_bf16_f32 v0, v0, s0
	ds_write_b16 v40, v0 offset:53632
	v_mul_f32_e32 v0, v27, v35
	v_cvt_pk_bf16_f32 v0, v0, s0
	v_rcp_f32_e32 v37, v37
	ds_write_b16 v40, v0 offset:53696
	v_mul_f32_e32 v0, v12, v36
	v_cvt_pk_bf16_f32 v0, v0, s0
	ds_write_b16 v40, v0 offset:54272
	v_mul_f32_e32 v0, v28, v36
	v_cvt_pk_bf16_f32 v0, v0, s0
	v_rcp_f32_e32 v38, v38
	ds_write_b16 v40, v0 offset:54336
	v_mul_f32_e32 v0, v13, v37
	v_cvt_pk_bf16_f32 v0, v0, s0
	ds_write_b16 v40, v0 offset:54400
	v_mul_f32_e32 v0, v29, v37
	v_cvt_pk_bf16_f32 v0, v0, s0
	v_rcp_f32_e32 v39, v39
	ds_write_b16 v40, v0 offset:54464
	v_mul_f32_e32 v0, v14, v38
	v_cvt_pk_bf16_f32 v0, v0, s0
	ds_write_b16 v40, v0 offset:54528
	v_mul_f32_e32 v0, v30, v38
	v_cvt_pk_bf16_f32 v0, v0, s0
	ds_write_b16 v40, v0 offset:54592
	v_mul_f32_e32 v0, v15, v39
	v_cvt_pk_bf16_f32 v0, v0, s0
	ds_write_b16 v40, v0 offset:54656
	v_mul_f32_e32 v0, v31, v39
	v_and_b32_e32 v6, 7, v194
	v_cvt_pk_bf16_f32 v0, v0, s0
	v_lshlrev_b32_e32 v128, 4, v6
	ds_write_b16 v40, v0 offset:54720
	v_lshrrev_b32_e32 v5, 3, v195
	v_add_u32_e32 v7, s14, v128
	s_waitcnt lgkmcnt(0)
	v_lshl_add_u32 v9, v5, 7, v7
	v_and_b32_e32 v3, 64, v230
	ds_read_b128 v[10:13], v9 offset:51200
	v_xor_b32_e32 v2, 1, v230
	v_add_u32_e32 v4, 64, v3
	v_cmp_lt_i32_e32 vcc, v2, v4
	v_xor_b32_e32 v3, 2, v230
	v_xor_b32_e32 v8, 4, v230
	v_cndmask_b32_e32 v2, v230, v2, vcc
	v_cmp_lt_i32_e32 vcc, v3, v4
	s_waitcnt lgkmcnt(0)
	v_and_b32_e32 v9, 0xffff0000, v11
	v_mul_f32_e32 v9, v9, v9
	v_cndmask_b32_e32 v3, v230, v3, vcc
	v_cmp_lt_i32_e32 vcc, v8, v4
	v_lshlrev_b32_e32 v2, 2, v2
	v_lshlrev_b32_e32 v3, 2, v3
	v_cndmask_b32_e32 v4, v230, v8, vcc
	v_and_b32_e32 v8, 0xffff0000, v10
	v_cmp_eq_u32_e32 vcc, 0, v6
	v_lshlrev_b32_e32 v6, 16, v10
	v_mul_f32_e32 v8, v8, v8
	v_fmac_f32_e32 v8, v6, v6
	v_lshlrev_b32_e32 v6, 16, v11
	v_fmac_f32_e32 v9, v6, v6
	v_add_f32_e32 v6, v8, v9
	v_and_b32_e32 v9, 0xffff0000, v12
	v_lshlrev_b32_e32 v8, 16, v12
	v_mul_f32_e32 v9, v9, v9
	v_fmac_f32_e32 v9, v8, v8
	v_add_f32_e32 v6, v9, v6
	v_and_b32_e32 v9, 0xffff0000, v13
	v_lshlrev_b32_e32 v8, 16, v13
	v_mul_f32_e32 v9, v9, v9
	v_fmac_f32_e32 v9, v8, v8
	v_add_f32_e32 v6, v9, v6
	ds_bpermute_b32 v8, v2, v6
	s_add_u32 s4, s4, s44
	s_addc_u32 s5, s5, s45
	v_lshl_add_u64 v[0:1], s[4:5], 0, v[128:129]
	s_lshl_b64 s[4:5], s[42:43], 2
	s_waitcnt lgkmcnt(0)
	v_add_f32_e32 v6, v6, v8
	ds_bpermute_b32 v8, v3, v6
	v_lshlrev_b32_e32 v4, 2, v4
	s_add_u32 s14, s8, s4
	s_addc_u32 s15, s9, s5
	s_lshl_b64 s[4:5], s[34:35], 2
	s_waitcnt lgkmcnt(0)
	v_add_f32_e32 v8, v6, v8
	ds_bpermute_b32 v9, v4, v8
	s_add_u32 s14, s14, s4
	s_addc_u32 s15, s15, s5
	s_lshl_b64 s[4:5], s[40:41], 2
	s_add_u32 s40, s14, s4
	v_lshlrev_b32_e32 v128, 11, v5
	s_addc_u32 s41, s15, s5
	v_lshl_add_u64 v[14:15], v[0:1], 0, v[128:129]
	v_lshlrev_b32_e32 v6, 2, v5
	global_store_dwordx4 v[14:15], v[10:13], off
	s_and_saveexec_b64 s[4:5], vcc
	s_mov_b32 s13, s95
	s_cbranch_execz .LBB0_455
	s_waitcnt lgkmcnt(0)
	v_add_f32_e32 v8, v8, v9
	global_atomic_add_f32 v6, v8, s[40:41]
